# sel radix passes: skip LDS atomic when no lane matches prefix
# speedup vs baseline: 1.0003x; 1.0003x over previous
; #define SEL_HADD(idx_) __hip_atomic_fetch_add(&hist[(idx_)], 1u, __ATOMIC_RELAXED, __HIP_MEMORY_SCOPE_WORKGROUP)
; __device__ __forceinline__ void sel_unit(LAS char* lds, int b, int u, const bf16_t* QI, const bf16_t* KIDX, const float* WIDX, unsigned long long* MASK) {
;     ...
;     for (int pass = 1; pass < 4; ++pass) {
;         const int shift = 24 - 8 * pass;
;         { const int t_ = opaque_tid(); for (int i = t_; i < 4096; i += 512) hist[i] = 0u; }
;         __syncthreads();
;         const unsigned pf = pref[q16];
;         unsigned zz = 0u; asm volatile("" : "+v"(zz));
; #pragma unroll
;         for (int j = 0; j < 8; ++j) if (j < nj) {
; #pragma unroll
;             for (int kb = 0; kb < 4; ++kb)
; #pragma unroll
;                 for (int i = 0; i < 4; ++i) { const unsigned k = sc[j][kb][i] | zz; SEL_HADD((((k >> (shift + 8)) == pf) ? ((k >> shift) & 255u) * 16 : 4096u) + q16); __builtin_amdgcn_sched_barrier(0); }
;         }
.LBB0_709:
	s_or_b64 exec, exec, s[2:3]
	s_waitcnt lgkmcnt(0)
	s_barrier
	ds_read_b32 v2, v60 offset:34880
	s_lshl_b32 s2, s21, 3
	s_sub_i32 s16, 24, s2
	v_mov_b32_e32 v3, 0
	s_sub_i32 s17, 32, s2
	s_and_b64 vcc, exec, s[22:23]
	s_cbranch_vccz .LBB0_711
	v_lshrrev_b32_e32 v5, s17, v62
	s_waitcnt lgkmcnt(0)
	v_cmp_eq_u32_e32 vcc, v5, v2
	s_cbranch_vccz .Lsel_skip_1
	v_lshrrev_b32_e32 v4, s16, v62
	v_lshlrev_b32_e32 v4, 4, v4
	v_and_b32_e32 v4, 0xff0, v4
	v_cndmask_b32_e32 v4, v203, v4, vcc
	v_lshl_add_u32 v4, v4, 2, v0
	ds_add_u32 v4, v205 offset:16384
.Lsel_skip_1:
	v_lshrrev_b32_e32 v5, s17, v61
	v_cmp_eq_u32_e32 vcc, v5, v2
	s_cbranch_vccz .Lsel_skip_2
	v_lshrrev_b32_e32 v4, s16, v61
	v_lshlrev_b32_e32 v4, 4, v4
	v_and_b32_e32 v4, 0xff0, v4
	v_cndmask_b32_e32 v4, v203, v4, vcc
	v_lshl_add_u32 v4, v4, 2, v0
	ds_add_u32 v4, v205 offset:16384
.Lsel_skip_2:
	v_lshrrev_b32_e32 v5, s17, v64
	v_cmp_eq_u32_e32 vcc, v5, v2
	s_cbranch_vccz .Lsel_skip_3
	v_lshrrev_b32_e32 v4, s16, v64
	v_lshlrev_b32_e32 v4, 4, v4
	v_and_b32_e32 v4, 0xff0, v4
	v_cndmask_b32_e32 v4, v203, v4, vcc
	v_lshl_add_u32 v4, v4, 2, v0
	ds_add_u32 v4, v205 offset:16384
.Lsel_skip_3:
	v_lshrrev_b32_e32 v5, s17, v63
	v_cmp_eq_u32_e32 vcc, v5, v2
	s_cbranch_vccz .Lsel_skip_4
	v_lshrrev_b32_e32 v4, s16, v63
	v_lshlrev_b32_e32 v4, 4, v4
	v_and_b32_e32 v4, 0xff0, v4
	v_cndmask_b32_e32 v4, v203, v4, vcc
	v_lshl_add_u32 v4, v4, 2, v0
	ds_add_u32 v4, v205 offset:16384
.Lsel_skip_4:
	v_lshrrev_b32_e32 v5, s17, v66
	v_cmp_eq_u32_e32 vcc, v5, v2
	s_cbranch_vccz .Lsel_skip_5
	v_lshrrev_b32_e32 v4, s16, v66
	v_lshlrev_b32_e32 v4, 4, v4
	v_and_b32_e32 v4, 0xff0, v4
	v_cndmask_b32_e32 v4, v203, v4, vcc
	v_lshl_add_u32 v4, v4, 2, v0
	ds_add_u32 v4, v205 offset:16384
.Lsel_skip_5:
	v_lshrrev_b32_e32 v5, s17, v65
	v_cmp_eq_u32_e32 vcc, v5, v2
	s_cbranch_vccz .Lsel_skip_6
	v_lshrrev_b32_e32 v4, s16, v65
	v_lshlrev_b32_e32 v4, 4, v4
	v_and_b32_e32 v4, 0xff0, v4
	v_cndmask_b32_e32 v4, v203, v4, vcc
	v_lshl_add_u32 v4, v4, 2, v0
	ds_add_u32 v4, v205 offset:16384
.Lsel_skip_6:
	v_lshrrev_b32_e32 v5, s17, v68
	v_cmp_eq_u32_e32 vcc, v5, v2
	s_cbranch_vccz .Lsel_skip_7
	v_lshrrev_b32_e32 v4, s16, v68
	v_lshlrev_b32_e32 v4, 4, v4
	v_and_b32_e32 v4, 0xff0, v4
	v_cndmask_b32_e32 v4, v203, v4, vcc
	v_lshl_add_u32 v4, v4, 2, v0
	ds_add_u32 v4, v205 offset:16384
.Lsel_skip_7:
	v_lshrrev_b32_e32 v5, s17, v67
	v_cmp_eq_u32_e32 vcc, v5, v2
	s_cbranch_vccz .Lsel_skip_8
	v_lshrrev_b32_e32 v4, s16, v67
	v_lshlrev_b32_e32 v4, 4, v4
	v_and_b32_e32 v4, 0xff0, v4
	v_cndmask_b32_e32 v4, v203, v4, vcc
	v_lshl_add_u32 v4, v4, 2, v0
	ds_add_u32 v4, v205 offset:16384
.Lsel_skip_8:
	v_lshrrev_b32_e32 v5, s17, v70
	v_cmp_eq_u32_e32 vcc, v5, v2
	s_cbranch_vccz .Lsel_skip_9
	v_lshrrev_b32_e32 v4, s16, v70
	v_lshlrev_b32_e32 v4, 4, v4
	v_and_b32_e32 v4, 0xff0, v4
	v_cndmask_b32_e32 v4, v203, v4, vcc
	v_lshl_add_u32 v4, v4, 2, v0
	ds_add_u32 v4, v205 offset:16384
.Lsel_skip_9:
	v_lshrrev_b32_e32 v5, s17, v69
	v_cmp_eq_u32_e32 vcc, v5, v2
	s_cbranch_vccz .Lsel_skip_10
	v_lshrrev_b32_e32 v4, s16, v69
	v_lshlrev_b32_e32 v4, 4, v4
	v_and_b32_e32 v4, 0xff0, v4
	v_cndmask_b32_e32 v4, v203, v4, vcc
	v_lshl_add_u32 v4, v4, 2, v0
	ds_add_u32 v4, v205 offset:16384
.Lsel_skip_10:
	v_lshrrev_b32_e32 v5, s17, v72
	v_cmp_eq_u32_e32 vcc, v5, v2
	s_cbranch_vccz .Lsel_skip_11
	v_lshrrev_b32_e32 v4, s16, v72
	v_lshlrev_b32_e32 v4, 4, v4
	v_and_b32_e32 v4, 0xff0, v4
	v_cndmask_b32_e32 v4, v203, v4, vcc
	v_lshl_add_u32 v4, v4, 2, v0
	ds_add_u32 v4, v205 offset:16384
.Lsel_skip_11:
	v_lshrrev_b32_e32 v5, s17, v71
	v_cmp_eq_u32_e32 vcc, v5, v2
	s_cbranch_vccz .Lsel_skip_12
	v_lshrrev_b32_e32 v4, s16, v71
	v_lshlrev_b32_e32 v4, 4, v4
	v_and_b32_e32 v4, 0xff0, v4
	v_cndmask_b32_e32 v4, v203, v4, vcc
	v_lshl_add_u32 v4, v4, 2, v0
	ds_add_u32 v4, v205 offset:16384
.Lsel_skip_12:
	v_lshrrev_b32_e32 v5, s17, v74
	v_cmp_eq_u32_e32 vcc, v5, v2
	s_cbranch_vccz .Lsel_skip_13
	v_lshrrev_b32_e32 v4, s16, v74
	v_lshlrev_b32_e32 v4, 4, v4
	v_and_b32_e32 v4, 0xff0, v4
	v_cndmask_b32_e32 v4, v203, v4, vcc
	v_lshl_add_u32 v4, v4, 2, v0
	ds_add_u32 v4, v205 offset:16384
.Lsel_skip_13:
	v_lshrrev_b32_e32 v5, s17, v73
	v_cmp_eq_u32_e32 vcc, v5, v2
	s_cbranch_vccz .Lsel_skip_14
	v_lshrrev_b32_e32 v4, s16, v73
	v_lshlrev_b32_e32 v4, 4, v4
	v_and_b32_e32 v4, 0xff0, v4
	v_cndmask_b32_e32 v4, v203, v4, vcc
	v_lshl_add_u32 v4, v4, 2, v0
	ds_add_u32 v4, v205 offset:16384
.Lsel_skip_14:
	v_lshrrev_b32_e32 v5, s17, v76
	v_cmp_eq_u32_e32 vcc, v5, v2
	s_cbranch_vccz .Lsel_skip_15
	v_lshrrev_b32_e32 v4, s16, v76
	v_lshlrev_b32_e32 v4, 4, v4
	v_and_b32_e32 v4, 0xff0, v4
	v_cndmask_b32_e32 v4, v203, v4, vcc
	v_lshl_add_u32 v4, v4, 2, v0
	ds_add_u32 v4, v205 offset:16384
.Lsel_skip_15:
	v_lshrrev_b32_e32 v5, s17, v75
	v_cmp_eq_u32_e32 vcc, v5, v2
	s_cbranch_vccz .Lsel_skip_16
	v_lshrrev_b32_e32 v4, s16, v75
	v_lshlrev_b32_e32 v4, 4, v4
	v_and_b32_e32 v4, 0xff0, v4
	v_cndmask_b32_e32 v4, v203, v4, vcc
	v_lshl_add_u32 v4, v4, 2, v0
	ds_add_u32 v4, v205 offset:16384
; #define SEL_HADD(idx_) __hip_atomic_fetch_add(&hist[(idx_)], 1u, __ATOMIC_RELAXED, __HIP_MEMORY_SCOPE_WORKGROUP)
; __device__ __forceinline__ void sel_unit(LAS char* lds, int b, int u, const bf16_t* QI, const bf16_t* KIDX, const float* WIDX, unsigned long long* MASK) {
;     ...
;     for (int pass = 1; pass < 4; ++pass) {
;         const int shift = 24 - 8 * pass;
;         { const int t_ = opaque_tid(); for (int i = t_; i < 4096; i += 512) hist[i] = 0u; }
;         __syncthreads();
;         const unsigned pf = pref[q16];
;         unsigned zz = 0u; asm volatile("" : "+v"(zz));
; #pragma unroll
;         for (int j = 0; j < 8; ++j) if (j < nj) {
; #pragma unroll
;             for (int kb = 0; kb < 4; ++kb)
; #pragma unroll
;                 for (int i = 0; i < 4; ++i) { const unsigned k = sc[j][kb][i] | zz; SEL_HADD((((k >> (shift + 8)) == pf) ? ((k >> shift) & 255u) * 16 : 4096u) + q16); __builtin_amdgcn_sched_barrier(0); }
;         }
.Lsel_skip_16:
.LBB0_711:
	v_cndmask_b32_e64 v4, 0, 1, s[18:19]
	v_cmp_ne_u32_e64 s[2:3], 1, v4
	s_andn2_b64 vcc, exec, s[18:19]
	s_cbranch_vccnz .LBB0_741
	v_lshrrev_b32_e32 v5, s17, v78
	s_waitcnt lgkmcnt(0)
	v_cmp_eq_u32_e32 vcc, v5, v2
	s_cbranch_vccz .Lsel_skip_17
	v_lshrrev_b32_e32 v4, s16, v78
	v_lshlrev_b32_e32 v4, 4, v4
	v_and_b32_e32 v4, 0xff0, v4
	v_cndmask_b32_e32 v4, v203, v4, vcc
	v_lshl_add_u32 v4, v4, 2, v0
	ds_add_u32 v4, v205 offset:16384
.Lsel_skip_17:
	v_lshrrev_b32_e32 v5, s17, v77
	v_cmp_eq_u32_e32 vcc, v5, v2
	s_cbranch_vccz .Lsel_skip_18
	v_lshrrev_b32_e32 v4, s16, v77
	v_lshlrev_b32_e32 v4, 4, v4
	v_and_b32_e32 v4, 0xff0, v4
	v_cndmask_b32_e32 v4, v203, v4, vcc
	v_lshl_add_u32 v4, v4, 2, v0
	ds_add_u32 v4, v205 offset:16384
.Lsel_skip_18:
	v_lshrrev_b32_e32 v5, s17, v80
	v_cmp_eq_u32_e32 vcc, v5, v2
	s_cbranch_vccz .Lsel_skip_19
	v_lshrrev_b32_e32 v4, s16, v80
	v_lshlrev_b32_e32 v4, 4, v4
	v_and_b32_e32 v4, 0xff0, v4
	v_cndmask_b32_e32 v4, v203, v4, vcc
	v_lshl_add_u32 v4, v4, 2, v0
	ds_add_u32 v4, v205 offset:16384
.Lsel_skip_19:
	v_lshrrev_b32_e32 v5, s17, v79
	v_cmp_eq_u32_e32 vcc, v5, v2
	s_cbranch_vccz .Lsel_skip_20
	v_lshrrev_b32_e32 v4, s16, v79
	v_lshlrev_b32_e32 v4, 4, v4
	v_and_b32_e32 v4, 0xff0, v4
	v_cndmask_b32_e32 v4, v203, v4, vcc
	v_lshl_add_u32 v4, v4, 2, v0
	ds_add_u32 v4, v205 offset:16384
.Lsel_skip_20:
	v_lshrrev_b32_e32 v5, s17, v82
	v_cmp_eq_u32_e32 vcc, v5, v2
	s_cbranch_vccz .Lsel_skip_21
	v_lshrrev_b32_e32 v4, s16, v82
	v_lshlrev_b32_e32 v4, 4, v4
	v_and_b32_e32 v4, 0xff0, v4
	v_cndmask_b32_e32 v4, v203, v4, vcc
	v_lshl_add_u32 v4, v4, 2, v0
	ds_add_u32 v4, v205 offset:16384
.Lsel_skip_21:
	v_lshrrev_b32_e32 v5, s17, v81
	v_cmp_eq_u32_e32 vcc, v5, v2
	s_cbranch_vccz .Lsel_skip_22
	v_lshrrev_b32_e32 v4, s16, v81
	v_lshlrev_b32_e32 v4, 4, v4
	v_and_b32_e32 v4, 0xff0, v4
	v_cndmask_b32_e32 v4, v203, v4, vcc
	v_lshl_add_u32 v4, v4, 2, v0
	ds_add_u32 v4, v205 offset:16384
.Lsel_skip_22:
	v_lshrrev_b32_e32 v5, s17, v84
	v_cmp_eq_u32_e32 vcc, v5, v2
	s_cbranch_vccz .Lsel_skip_23
	v_lshrrev_b32_e32 v4, s16, v84
	v_lshlrev_b32_e32 v4, 4, v4
	v_and_b32_e32 v4, 0xff0, v4
	v_cndmask_b32_e32 v4, v203, v4, vcc
	v_lshl_add_u32 v4, v4, 2, v0
	ds_add_u32 v4, v205 offset:16384
.Lsel_skip_23:
	v_lshrrev_b32_e32 v5, s17, v83
	v_cmp_eq_u32_e32 vcc, v5, v2
	s_cbranch_vccz .Lsel_skip_24
	v_lshrrev_b32_e32 v4, s16, v83
	v_lshlrev_b32_e32 v4, 4, v4
	v_and_b32_e32 v4, 0xff0, v4
	v_cndmask_b32_e32 v4, v203, v4, vcc
	v_lshl_add_u32 v4, v4, 2, v0
	ds_add_u32 v4, v205 offset:16384
.Lsel_skip_24:
	v_lshrrev_b32_e32 v5, s17, v86
	v_cmp_eq_u32_e32 vcc, v5, v2
	s_cbranch_vccz .Lsel_skip_25
	v_lshrrev_b32_e32 v4, s16, v86
	v_lshlrev_b32_e32 v4, 4, v4
	v_and_b32_e32 v4, 0xff0, v4
	v_cndmask_b32_e32 v4, v203, v4, vcc
	v_lshl_add_u32 v4, v4, 2, v0
	ds_add_u32 v4, v205 offset:16384
.Lsel_skip_25:
	v_lshrrev_b32_e32 v5, s17, v85
	v_cmp_eq_u32_e32 vcc, v5, v2
	s_cbranch_vccz .Lsel_skip_26
	v_lshrrev_b32_e32 v4, s16, v85
	v_lshlrev_b32_e32 v4, 4, v4
	v_and_b32_e32 v4, 0xff0, v4
	v_cndmask_b32_e32 v4, v203, v4, vcc
	v_lshl_add_u32 v4, v4, 2, v0
	ds_add_u32 v4, v205 offset:16384
.Lsel_skip_26:
	v_lshrrev_b32_e32 v5, s17, v88
	v_cmp_eq_u32_e32 vcc, v5, v2
	s_cbranch_vccz .Lsel_skip_27
	v_lshrrev_b32_e32 v4, s16, v88
	v_lshlrev_b32_e32 v4, 4, v4
	v_and_b32_e32 v4, 0xff0, v4
	v_cndmask_b32_e32 v4, v203, v4, vcc
	v_lshl_add_u32 v4, v4, 2, v0
	ds_add_u32 v4, v205 offset:16384
.Lsel_skip_27:
	v_lshrrev_b32_e32 v5, s17, v87
	v_cmp_eq_u32_e32 vcc, v5, v2
	s_cbranch_vccz .Lsel_skip_28
	v_lshrrev_b32_e32 v4, s16, v87
	v_lshlrev_b32_e32 v4, 4, v4
	v_and_b32_e32 v4, 0xff0, v4
	v_cndmask_b32_e32 v4, v203, v4, vcc
	v_lshl_add_u32 v4, v4, 2, v0
	ds_add_u32 v4, v205 offset:16384
.Lsel_skip_28:
	v_lshrrev_b32_e32 v5, s17, v90
	v_cmp_eq_u32_e32 vcc, v5, v2
	s_cbranch_vccz .Lsel_skip_29
	v_lshrrev_b32_e32 v4, s16, v90
	v_lshlrev_b32_e32 v4, 4, v4
	v_and_b32_e32 v4, 0xff0, v4
	v_cndmask_b32_e32 v4, v203, v4, vcc
	v_lshl_add_u32 v4, v4, 2, v0
	ds_add_u32 v4, v205 offset:16384
.Lsel_skip_29:
	v_lshrrev_b32_e32 v5, s17, v89
	v_cmp_eq_u32_e32 vcc, v5, v2
	s_cbranch_vccz .Lsel_skip_30
	v_lshrrev_b32_e32 v4, s16, v89
	v_lshlrev_b32_e32 v4, 4, v4
	v_and_b32_e32 v4, 0xff0, v4
	v_cndmask_b32_e32 v4, v203, v4, vcc
	v_lshl_add_u32 v4, v4, 2, v0
	ds_add_u32 v4, v205 offset:16384
.Lsel_skip_30:
	v_lshrrev_b32_e32 v5, s17, v92
	v_cmp_eq_u32_e32 vcc, v5, v2
	s_cbranch_vccz .Lsel_skip_31
	v_lshrrev_b32_e32 v4, s16, v92
	v_lshlrev_b32_e32 v4, 4, v4
	v_and_b32_e32 v4, 0xff0, v4
	v_cndmask_b32_e32 v4, v203, v4, vcc
	v_lshl_add_u32 v4, v4, 2, v0
	ds_add_u32 v4, v205 offset:16384
.Lsel_skip_31:
	v_lshrrev_b32_e32 v5, s17, v91
	v_cmp_eq_u32_e32 vcc, v5, v2
	s_cbranch_vccz .Lsel_skip_32
	v_lshrrev_b32_e32 v4, s16, v91
	v_lshlrev_b32_e32 v4, 4, v4
	v_and_b32_e32 v4, 0xff0, v4
	v_cndmask_b32_e32 v4, v203, v4, vcc
	v_lshl_add_u32 v4, v4, 2, v0
	ds_add_u32 v4, v205 offset:16384
.Lsel_skip_32:
	v_cndmask_b32_e64 v4, 0, 1, s[54:55]
	v_cmp_ne_u32_e64 s[4:5], 1, v4
	s_andn2_b64 vcc, exec, s[54:55]
	s_cbranch_vccz .LBB0_742

; #define SEL_HADD(idx_) __hip_atomic_fetch_add(&hist[(idx_)], 1u, __ATOMIC_RELAXED, __HIP_MEMORY_SCOPE_WORKGROUP)
; __device__ __forceinline__ void sel_unit(LAS char* lds, int b, int u, const bf16_t* QI, const bf16_t* KIDX, const float* WIDX, unsigned long long* MASK) {
;     ...
;     for (int pass = 1; pass < 4; ++pass) {
;         const int shift = 24 - 8 * pass;
;         { const int t_ = opaque_tid(); for (int i = t_; i < 4096; i += 512) hist[i] = 0u; }
;         __syncthreads();
;         const unsigned pf = pref[q16];
;         unsigned zz = 0u; asm volatile("" : "+v"(zz));
; #pragma unroll
;         for (int j = 0; j < 8; ++j) if (j < nj) {
; #pragma unroll
;             for (int kb = 0; kb < 4; ++kb)
; #pragma unroll
;                 for (int i = 0; i < 4; ++i) { const unsigned k = sc[j][kb][i] | zz; SEL_HADD((((k >> (shift + 8)) == pf) ? ((k >> shift) & 255u) * 16 : 4096u) + q16); __builtin_amdgcn_sched_barrier(0); }
;         }
.LBB0_714:
	v_lshrrev_b32_e32 v5, s17, v110
	s_waitcnt lgkmcnt(0)
	v_cmp_eq_u32_e32 vcc, v5, v2
	s_cbranch_vccz .Lsel_skip_33
	v_lshrrev_b32_e32 v4, s16, v110
	v_lshlrev_b32_e32 v4, 4, v4
	v_and_b32_e32 v4, 0xff0, v4
	v_cndmask_b32_e32 v4, v203, v4, vcc
	v_lshl_add_u32 v4, v4, 2, v0
	ds_add_u32 v4, v205 offset:16384
.Lsel_skip_33:
	v_lshrrev_b32_e32 v5, s17, v109
	v_cmp_eq_u32_e32 vcc, v5, v2
	s_cbranch_vccz .Lsel_skip_34
	v_lshrrev_b32_e32 v4, s16, v109
	v_lshlrev_b32_e32 v4, 4, v4
	v_and_b32_e32 v4, 0xff0, v4
	v_cndmask_b32_e32 v4, v203, v4, vcc
	v_lshl_add_u32 v4, v4, 2, v0
	ds_add_u32 v4, v205 offset:16384
.Lsel_skip_34:
	v_lshrrev_b32_e32 v5, s17, v112
	v_cmp_eq_u32_e32 vcc, v5, v2
	s_cbranch_vccz .Lsel_skip_35
	v_lshrrev_b32_e32 v4, s16, v112
	v_lshlrev_b32_e32 v4, 4, v4
	v_and_b32_e32 v4, 0xff0, v4
	v_cndmask_b32_e32 v4, v203, v4, vcc
	v_lshl_add_u32 v4, v4, 2, v0
	ds_add_u32 v4, v205 offset:16384
.Lsel_skip_35:
	v_lshrrev_b32_e32 v5, s17, v111
	v_cmp_eq_u32_e32 vcc, v5, v2
	s_cbranch_vccz .Lsel_skip_36
	v_lshrrev_b32_e32 v4, s16, v111
	v_lshlrev_b32_e32 v4, 4, v4
	v_and_b32_e32 v4, 0xff0, v4
	v_cndmask_b32_e32 v4, v203, v4, vcc
	v_lshl_add_u32 v4, v4, 2, v0
	ds_add_u32 v4, v205 offset:16384
.Lsel_skip_36:
	v_lshrrev_b32_e32 v5, s17, v114
	v_cmp_eq_u32_e32 vcc, v5, v2
	s_cbranch_vccz .Lsel_skip_37
	v_lshrrev_b32_e32 v4, s16, v114
	v_lshlrev_b32_e32 v4, 4, v4
	v_and_b32_e32 v4, 0xff0, v4
	v_cndmask_b32_e32 v4, v203, v4, vcc
	v_lshl_add_u32 v4, v4, 2, v0
	ds_add_u32 v4, v205 offset:16384
.Lsel_skip_37:
	v_lshrrev_b32_e32 v5, s17, v113
	v_cmp_eq_u32_e32 vcc, v5, v2
	s_cbranch_vccz .Lsel_skip_38
	v_lshrrev_b32_e32 v4, s16, v113
	v_lshlrev_b32_e32 v4, 4, v4
	v_and_b32_e32 v4, 0xff0, v4
	v_cndmask_b32_e32 v4, v203, v4, vcc
	v_lshl_add_u32 v4, v4, 2, v0
	ds_add_u32 v4, v205 offset:16384
.Lsel_skip_38:
	v_lshrrev_b32_e32 v5, s17, v116
	v_cmp_eq_u32_e32 vcc, v5, v2
	s_cbranch_vccz .Lsel_skip_39
	v_lshrrev_b32_e32 v4, s16, v116
	v_lshlrev_b32_e32 v4, 4, v4
	v_and_b32_e32 v4, 0xff0, v4
	v_cndmask_b32_e32 v4, v203, v4, vcc
	v_lshl_add_u32 v4, v4, 2, v0
	ds_add_u32 v4, v205 offset:16384
.Lsel_skip_39:
	v_lshrrev_b32_e32 v5, s17, v115
	v_cmp_eq_u32_e32 vcc, v5, v2
	s_cbranch_vccz .Lsel_skip_40
	v_lshrrev_b32_e32 v4, s16, v115
	v_lshlrev_b32_e32 v4, 4, v4
	v_and_b32_e32 v4, 0xff0, v4
	v_cndmask_b32_e32 v4, v203, v4, vcc
	v_lshl_add_u32 v4, v4, 2, v0
	ds_add_u32 v4, v205 offset:16384
.Lsel_skip_40:
	v_lshrrev_b32_e32 v5, s17, v118
	v_cmp_eq_u32_e32 vcc, v5, v2
	s_cbranch_vccz .Lsel_skip_41
	v_lshrrev_b32_e32 v4, s16, v118
	v_lshlrev_b32_e32 v4, 4, v4
	v_and_b32_e32 v4, 0xff0, v4
	v_cndmask_b32_e32 v4, v203, v4, vcc
	v_lshl_add_u32 v4, v4, 2, v0
	ds_add_u32 v4, v205 offset:16384
.Lsel_skip_41:
	v_lshrrev_b32_e32 v5, s17, v117
	v_cmp_eq_u32_e32 vcc, v5, v2
	s_cbranch_vccz .Lsel_skip_42
	v_lshrrev_b32_e32 v4, s16, v117
	v_lshlrev_b32_e32 v4, 4, v4
	v_and_b32_e32 v4, 0xff0, v4
	v_cndmask_b32_e32 v4, v203, v4, vcc
	v_lshl_add_u32 v4, v4, 2, v0
	ds_add_u32 v4, v205 offset:16384
.Lsel_skip_42:
	v_lshrrev_b32_e32 v5, s17, v120
	v_cmp_eq_u32_e32 vcc, v5, v2
	s_cbranch_vccz .Lsel_skip_43
	v_lshrrev_b32_e32 v4, s16, v120
	v_lshlrev_b32_e32 v4, 4, v4
	v_and_b32_e32 v4, 0xff0, v4
	v_cndmask_b32_e32 v4, v203, v4, vcc
	v_lshl_add_u32 v4, v4, 2, v0
	ds_add_u32 v4, v205 offset:16384
.Lsel_skip_43:
	v_lshrrev_b32_e32 v5, s17, v119
	v_cmp_eq_u32_e32 vcc, v5, v2
	s_cbranch_vccz .Lsel_skip_44
	v_lshrrev_b32_e32 v4, s16, v119
	v_lshlrev_b32_e32 v4, 4, v4
	v_and_b32_e32 v4, 0xff0, v4
	v_cndmask_b32_e32 v4, v203, v4, vcc
	v_lshl_add_u32 v4, v4, 2, v0
	ds_add_u32 v4, v205 offset:16384
.Lsel_skip_44:
	v_lshrrev_b32_e32 v5, s17, v122
	v_cmp_eq_u32_e32 vcc, v5, v2
	s_cbranch_vccz .Lsel_skip_45
	v_lshrrev_b32_e32 v4, s16, v122
	v_lshlrev_b32_e32 v4, 4, v4
	v_and_b32_e32 v4, 0xff0, v4
	v_cndmask_b32_e32 v4, v203, v4, vcc
	v_lshl_add_u32 v4, v4, 2, v0
	ds_add_u32 v4, v205 offset:16384
.Lsel_skip_45:
	v_lshrrev_b32_e32 v5, s17, v121
	v_cmp_eq_u32_e32 vcc, v5, v2
	s_cbranch_vccz .Lsel_skip_46
	v_lshrrev_b32_e32 v4, s16, v121
	v_lshlrev_b32_e32 v4, 4, v4
	v_and_b32_e32 v4, 0xff0, v4
	v_cndmask_b32_e32 v4, v203, v4, vcc
	v_lshl_add_u32 v4, v4, 2, v0
	ds_add_u32 v4, v205 offset:16384
.Lsel_skip_46:
	v_lshrrev_b32_e32 v5, s17, v124
	v_cmp_eq_u32_e32 vcc, v5, v2
	s_cbranch_vccz .Lsel_skip_47
	v_lshrrev_b32_e32 v4, s16, v124
	v_lshlrev_b32_e32 v4, 4, v4
	v_and_b32_e32 v4, 0xff0, v4
	v_cndmask_b32_e32 v4, v203, v4, vcc
	v_lshl_add_u32 v4, v4, 2, v0
	ds_add_u32 v4, v205 offset:16384
.Lsel_skip_47:
	v_lshrrev_b32_e32 v5, s17, v123
	v_cmp_eq_u32_e32 vcc, v5, v2
	s_cbranch_vccz .Lsel_skip_48
	v_lshrrev_b32_e32 v4, s16, v123
	v_lshlrev_b32_e32 v4, 4, v4
	v_and_b32_e32 v4, 0xff0, v4
	v_cndmask_b32_e32 v4, v203, v4, vcc
	v_lshl_add_u32 v4, v4, 2, v0
	ds_add_u32 v4, v205 offset:16384
.Lsel_skip_48:
	v_cndmask_b32_e64 v4, 0, 1, s[24:25]
	v_cmp_ne_u32_e64 s[8:9], 1, v4
	s_andn2_b64 vcc, exec, s[24:25]
	s_cbranch_vccz .LBB0_744

; #define SEL_HADD(idx_) __hip_atomic_fetch_add(&hist[(idx_)], 1u, __ATOMIC_RELAXED, __HIP_MEMORY_SCOPE_WORKGROUP)
; __device__ __forceinline__ void sel_unit(LAS char* lds, int b, int u, const bf16_t* QI, const bf16_t* KIDX, const float* WIDX, unsigned long long* MASK) {
;     ...
;     for (int pass = 1; pass < 4; ++pass) {
;         const int shift = 24 - 8 * pass;
;         { const int t_ = opaque_tid(); for (int i = t_; i < 4096; i += 512) hist[i] = 0u; }
;         __syncthreads();
;         const unsigned pf = pref[q16];
;         unsigned zz = 0u; asm volatile("" : "+v"(zz));
; #pragma unroll
;         for (int j = 0; j < 8; ++j) if (j < nj) {
; #pragma unroll
;             for (int kb = 0; kb < 4; ++kb)
; #pragma unroll
;                 for (int i = 0; i < 4; ++i) { const unsigned k = sc[j][kb][i] | zz; SEL_HADD((((k >> (shift + 8)) == pf) ? ((k >> shift) & 255u) * 16 : 4096u) + q16); __builtin_amdgcn_sched_barrier(0); }
;         }
.LBB0_716:
	v_lshrrev_b32_e32 v5, s17, v143
	s_waitcnt lgkmcnt(0)
	v_cmp_eq_u32_e32 vcc, v5, v2
	s_cbranch_vccz .Lsel_skip_49
	v_lshrrev_b32_e32 v4, s16, v143
	v_lshlrev_b32_e32 v4, 4, v4
	v_and_b32_e32 v4, 0xff0, v4
	v_cndmask_b32_e32 v4, v203, v4, vcc
	v_lshl_add_u32 v4, v4, 2, v0
	ds_add_u32 v4, v205 offset:16384
.Lsel_skip_49:
	v_lshrrev_b32_e32 v5, s17, v142
	v_cmp_eq_u32_e32 vcc, v5, v2
	s_cbranch_vccz .Lsel_skip_50
	v_lshrrev_b32_e32 v4, s16, v142
	v_lshlrev_b32_e32 v4, 4, v4
	v_and_b32_e32 v4, 0xff0, v4
	v_cndmask_b32_e32 v4, v203, v4, vcc
	v_lshl_add_u32 v4, v4, 2, v0
	ds_add_u32 v4, v205 offset:16384
.Lsel_skip_50:
	v_lshrrev_b32_e32 v5, s17, v145
	v_cmp_eq_u32_e32 vcc, v5, v2
	s_cbranch_vccz .Lsel_skip_51
	v_lshrrev_b32_e32 v4, s16, v145
	v_lshlrev_b32_e32 v4, 4, v4
	v_and_b32_e32 v4, 0xff0, v4
	v_cndmask_b32_e32 v4, v203, v4, vcc
	v_lshl_add_u32 v4, v4, 2, v0
	ds_add_u32 v4, v205 offset:16384
.Lsel_skip_51:
	v_lshrrev_b32_e32 v5, s17, v144
	v_cmp_eq_u32_e32 vcc, v5, v2
	s_cbranch_vccz .Lsel_skip_52
	v_lshrrev_b32_e32 v4, s16, v144
	v_lshlrev_b32_e32 v4, 4, v4
	v_and_b32_e32 v4, 0xff0, v4
	v_cndmask_b32_e32 v4, v203, v4, vcc
	v_lshl_add_u32 v4, v4, 2, v0
	ds_add_u32 v4, v205 offset:16384
.Lsel_skip_52:
	v_lshrrev_b32_e32 v5, s17, v147
	v_cmp_eq_u32_e32 vcc, v5, v2
	s_cbranch_vccz .Lsel_skip_53
	v_lshrrev_b32_e32 v4, s16, v147
	v_lshlrev_b32_e32 v4, 4, v4
	v_and_b32_e32 v4, 0xff0, v4
	v_cndmask_b32_e32 v4, v203, v4, vcc
	v_lshl_add_u32 v4, v4, 2, v0
	ds_add_u32 v4, v205 offset:16384
.Lsel_skip_53:
	v_lshrrev_b32_e32 v5, s17, v146
	v_cmp_eq_u32_e32 vcc, v5, v2
	s_cbranch_vccz .Lsel_skip_54
	v_lshrrev_b32_e32 v4, s16, v146
	v_lshlrev_b32_e32 v4, 4, v4
	v_and_b32_e32 v4, 0xff0, v4
	v_cndmask_b32_e32 v4, v203, v4, vcc
	v_lshl_add_u32 v4, v4, 2, v0
	ds_add_u32 v4, v205 offset:16384
.Lsel_skip_54:
	v_lshrrev_b32_e32 v5, s17, v149
	v_cmp_eq_u32_e32 vcc, v5, v2
	s_cbranch_vccz .Lsel_skip_55
	v_lshrrev_b32_e32 v4, s16, v149
	v_lshlrev_b32_e32 v4, 4, v4
	v_and_b32_e32 v4, 0xff0, v4
	v_cndmask_b32_e32 v4, v203, v4, vcc
	v_lshl_add_u32 v4, v4, 2, v0
	ds_add_u32 v4, v205 offset:16384
.Lsel_skip_55:
	v_lshrrev_b32_e32 v5, s17, v148
	v_cmp_eq_u32_e32 vcc, v5, v2
	s_cbranch_vccz .Lsel_skip_56
	v_lshrrev_b32_e32 v4, s16, v148
	v_lshlrev_b32_e32 v4, 4, v4
	v_and_b32_e32 v4, 0xff0, v4
	v_cndmask_b32_e32 v4, v203, v4, vcc
	v_lshl_add_u32 v4, v4, 2, v0
	ds_add_u32 v4, v205 offset:16384
.Lsel_skip_56:
	v_lshrrev_b32_e32 v5, s17, v178
	v_cmp_eq_u32_e32 vcc, v5, v2
	s_cbranch_vccz .Lsel_skip_57
	v_lshrrev_b32_e32 v4, s16, v178
	v_lshlrev_b32_e32 v4, 4, v4
	v_and_b32_e32 v4, 0xff0, v4
	v_cndmask_b32_e32 v4, v203, v4, vcc
	v_lshl_add_u32 v4, v4, 2, v0
	ds_add_u32 v4, v205 offset:16384
.Lsel_skip_57:
	v_lshrrev_b32_e32 v5, s17, v177
	v_cmp_eq_u32_e32 vcc, v5, v2
	s_cbranch_vccz .Lsel_skip_58
	v_lshrrev_b32_e32 v4, s16, v177
	v_lshlrev_b32_e32 v4, 4, v4
	v_and_b32_e32 v4, 0xff0, v4
	v_cndmask_b32_e32 v4, v203, v4, vcc
	v_lshl_add_u32 v4, v4, 2, v0
	ds_add_u32 v4, v205 offset:16384
.Lsel_skip_58:
	v_lshrrev_b32_e32 v5, s17, v186
	v_cmp_eq_u32_e32 vcc, v5, v2
	s_cbranch_vccz .Lsel_skip_59
	v_lshrrev_b32_e32 v4, s16, v186
	v_lshlrev_b32_e32 v4, 4, v4
	v_and_b32_e32 v4, 0xff0, v4
	v_cndmask_b32_e32 v4, v203, v4, vcc
	v_lshl_add_u32 v4, v4, 2, v0
	ds_add_u32 v4, v205 offset:16384
.Lsel_skip_59:
	v_lshrrev_b32_e32 v5, s17, v181
	v_cmp_eq_u32_e32 vcc, v5, v2
	s_cbranch_vccz .Lsel_skip_60
	v_lshrrev_b32_e32 v4, s16, v181
	v_lshlrev_b32_e32 v4, 4, v4
	v_and_b32_e32 v4, 0xff0, v4
	v_cndmask_b32_e32 v4, v203, v4, vcc
	v_lshl_add_u32 v4, v4, 2, v0
	ds_add_u32 v4, v205 offset:16384
.Lsel_skip_60:
	v_lshrrev_b32_e32 v5, s17, v188
	v_cmp_eq_u32_e32 vcc, v5, v2
	s_cbranch_vccz .Lsel_skip_61
	v_lshrrev_b32_e32 v4, s16, v188
	v_lshlrev_b32_e32 v4, 4, v4
	v_and_b32_e32 v4, 0xff0, v4
	v_cndmask_b32_e32 v4, v203, v4, vcc
	v_lshl_add_u32 v4, v4, 2, v0
	ds_add_u32 v4, v205 offset:16384
.Lsel_skip_61:
	v_lshrrev_b32_e32 v5, s17, v187
	v_cmp_eq_u32_e32 vcc, v5, v2
	s_cbranch_vccz .Lsel_skip_62
	v_lshrrev_b32_e32 v4, s16, v187
	v_lshlrev_b32_e32 v4, 4, v4
	v_and_b32_e32 v4, 0xff0, v4
	v_cndmask_b32_e32 v4, v203, v4, vcc
	v_lshl_add_u32 v4, v4, 2, v0
	ds_add_u32 v4, v205 offset:16384
.Lsel_skip_62:
	v_lshrrev_b32_e32 v5, s17, v190
	v_cmp_eq_u32_e32 vcc, v5, v2
	s_cbranch_vccz .Lsel_skip_63
	v_lshrrev_b32_e32 v4, s16, v190
	v_lshlrev_b32_e32 v4, 4, v4
	v_and_b32_e32 v4, 0xff0, v4
	v_cndmask_b32_e32 v4, v203, v4, vcc
	v_lshl_add_u32 v4, v4, 2, v0
	ds_add_u32 v4, v205 offset:16384
.Lsel_skip_63:
	v_lshrrev_b32_e32 v5, s17, v189
	v_cmp_eq_u32_e32 vcc, v5, v2
	s_cbranch_vccz .Lsel_skip_64
	v_lshrrev_b32_e32 v4, s16, v189
	v_lshlrev_b32_e32 v4, 4, v4
	v_and_b32_e32 v4, 0xff0, v4
	v_cndmask_b32_e32 v4, v203, v4, vcc
	v_lshl_add_u32 v4, v4, 2, v0
	ds_add_u32 v4, v205 offset:16384
.Lsel_skip_64:
	v_cndmask_b32_e64 v4, 0, 1, s[0:1]
	v_cmp_ne_u32_e64 s[12:13], 1, v4
	s_andn2_b64 vcc, exec, s[0:1]
	s_cbranch_vccz .LBB0_746

; #define SEL_HADD(idx_) __hip_atomic_fetch_add(&hist[(idx_)], 1u, __ATOMIC_RELAXED, __HIP_MEMORY_SCOPE_WORKGROUP)
; __device__ __forceinline__ void sel_unit(LAS char* lds, int b, int u, const bf16_t* QI, const bf16_t* KIDX, const float* WIDX, unsigned long long* MASK) {
;     ...
;     for (int pass = 1; pass < 4; ++pass) {
;         const int shift = 24 - 8 * pass;
;         { const int t_ = opaque_tid(); for (int i = t_; i < 4096; i += 512) hist[i] = 0u; }
;         __syncthreads();
;         const unsigned pf = pref[q16];
;         unsigned zz = 0u; asm volatile("" : "+v"(zz));
; #pragma unroll
;         for (int j = 0; j < 8; ++j) if (j < nj) {
; #pragma unroll
;             for (int kb = 0; kb < 4; ++kb)
; #pragma unroll
;                 for (int i = 0; i < 4; ++i) { const unsigned k = sc[j][kb][i] | zz; SEL_HADD((((k >> (shift + 8)) == pf) ? ((k >> shift) & 255u) * 16 : 4096u) + q16); __builtin_amdgcn_sched_barrier(0); }
;         }
.LBB0_718:
	v_lshrrev_b32_e32 v5, s17, v222
	s_waitcnt lgkmcnt(0)
	v_cmp_eq_u32_e32 vcc, v5, v2
	s_cbranch_vccz .Lsel_skip_65
	v_lshrrev_b32_e32 v4, s16, v222
	v_lshlrev_b32_e32 v4, 4, v4
	v_and_b32_e32 v4, 0xff0, v4
	v_cndmask_b32_e32 v4, v203, v4, vcc
	v_lshl_add_u32 v4, v4, 2, v0
	ds_add_u32 v4, v205 offset:16384
.Lsel_skip_65:
	v_lshrrev_b32_e32 v5, s17, v221
	v_cmp_eq_u32_e32 vcc, v5, v2
	s_cbranch_vccz .Lsel_skip_66
	v_lshrrev_b32_e32 v4, s16, v221
	v_lshlrev_b32_e32 v4, 4, v4
	v_and_b32_e32 v4, 0xff0, v4
	v_cndmask_b32_e32 v4, v203, v4, vcc
	v_lshl_add_u32 v4, v4, 2, v0
	ds_add_u32 v4, v205 offset:16384
.Lsel_skip_66:
	v_lshrrev_b32_e32 v5, s17, v224
	v_cmp_eq_u32_e32 vcc, v5, v2
	s_cbranch_vccz .Lsel_skip_67
	v_lshrrev_b32_e32 v4, s16, v224
	v_lshlrev_b32_e32 v4, 4, v4
	v_and_b32_e32 v4, 0xff0, v4
	v_cndmask_b32_e32 v4, v203, v4, vcc
	v_lshl_add_u32 v4, v4, 2, v0
	ds_add_u32 v4, v205 offset:16384
.Lsel_skip_67:
	v_lshrrev_b32_e32 v5, s17, v223
	v_cmp_eq_u32_e32 vcc, v5, v2
	s_cbranch_vccz .Lsel_skip_68
	v_lshrrev_b32_e32 v4, s16, v223
	v_lshlrev_b32_e32 v4, 4, v4
	v_and_b32_e32 v4, 0xff0, v4
	v_cndmask_b32_e32 v4, v203, v4, vcc
	v_lshl_add_u32 v4, v4, 2, v0
	ds_add_u32 v4, v205 offset:16384
.Lsel_skip_68:
	v_lshrrev_b32_e32 v5, s17, v226
	v_cmp_eq_u32_e32 vcc, v5, v2
	s_cbranch_vccz .Lsel_skip_69
	v_lshrrev_b32_e32 v4, s16, v226
	v_lshlrev_b32_e32 v4, 4, v4
	v_and_b32_e32 v4, 0xff0, v4
	v_cndmask_b32_e32 v4, v203, v4, vcc
	v_lshl_add_u32 v4, v4, 2, v0
	ds_add_u32 v4, v205 offset:16384
.Lsel_skip_69:
	v_lshrrev_b32_e32 v5, s17, v225
	v_cmp_eq_u32_e32 vcc, v5, v2
	s_cbranch_vccz .Lsel_skip_70
	v_lshrrev_b32_e32 v4, s16, v225
	v_lshlrev_b32_e32 v4, 4, v4
	v_and_b32_e32 v4, 0xff0, v4
	v_cndmask_b32_e32 v4, v203, v4, vcc
	v_lshl_add_u32 v4, v4, 2, v0
	ds_add_u32 v4, v205 offset:16384
.Lsel_skip_70:
	v_lshrrev_b32_e32 v5, s17, v228
	v_cmp_eq_u32_e32 vcc, v5, v2
	s_cbranch_vccz .Lsel_skip_71
	v_lshrrev_b32_e32 v4, s16, v228
	v_lshlrev_b32_e32 v4, 4, v4
	v_and_b32_e32 v4, 0xff0, v4
	v_cndmask_b32_e32 v4, v203, v4, vcc
	v_lshl_add_u32 v4, v4, 2, v0
	ds_add_u32 v4, v205 offset:16384
.Lsel_skip_71:
	v_lshrrev_b32_e32 v5, s17, v227
	v_cmp_eq_u32_e32 vcc, v5, v2
	s_cbranch_vccz .Lsel_skip_72
	v_lshrrev_b32_e32 v4, s16, v227
	v_lshlrev_b32_e32 v4, 4, v4
	v_and_b32_e32 v4, 0xff0, v4
	v_cndmask_b32_e32 v4, v203, v4, vcc
	v_lshl_add_u32 v4, v4, 2, v0
	ds_add_u32 v4, v205 offset:16384
.Lsel_skip_72:
	v_lshrrev_b32_e32 v5, s17, v11
	v_cmp_eq_u32_e32 vcc, v5, v2
	s_cbranch_vccz .Lsel_skip_73
	v_lshrrev_b32_e32 v4, s16, v11
	v_lshlrev_b32_e32 v4, 4, v4
	v_and_b32_e32 v4, 0xff0, v4
	v_cndmask_b32_e32 v4, v203, v4, vcc
	v_lshl_add_u32 v4, v4, 2, v0
	ds_add_u32 v4, v205 offset:16384
.Lsel_skip_73:
	v_lshrrev_b32_e32 v5, s17, v10
	v_cmp_eq_u32_e32 vcc, v5, v2
	s_cbranch_vccz .Lsel_skip_74
	v_lshrrev_b32_e32 v4, s16, v10
	v_lshlrev_b32_e32 v4, 4, v4
	v_and_b32_e32 v4, 0xff0, v4
	v_cndmask_b32_e32 v4, v203, v4, vcc
	v_lshl_add_u32 v4, v4, 2, v0
	ds_add_u32 v4, v205 offset:16384
.Lsel_skip_74:
	v_lshrrev_b32_e32 v5, s17, v13
	v_cmp_eq_u32_e32 vcc, v5, v2
	s_cbranch_vccz .Lsel_skip_75
	v_lshrrev_b32_e32 v4, s16, v13
	v_lshlrev_b32_e32 v4, 4, v4
	v_and_b32_e32 v4, 0xff0, v4
	v_cndmask_b32_e32 v4, v203, v4, vcc
	v_lshl_add_u32 v4, v4, 2, v0
	ds_add_u32 v4, v205 offset:16384
.Lsel_skip_75:
	v_lshrrev_b32_e32 v5, s17, v12
	v_cmp_eq_u32_e32 vcc, v5, v2
	s_cbranch_vccz .Lsel_skip_76
	v_lshrrev_b32_e32 v4, s16, v12
	v_lshlrev_b32_e32 v4, 4, v4
	v_and_b32_e32 v4, 0xff0, v4
	v_cndmask_b32_e32 v4, v203, v4, vcc
	v_lshl_add_u32 v4, v4, 2, v0
	ds_add_u32 v4, v205 offset:16384
.Lsel_skip_76:
	v_lshrrev_b32_e32 v5, s17, v15
	v_cmp_eq_u32_e32 vcc, v5, v2
	s_cbranch_vccz .Lsel_skip_77
	v_lshrrev_b32_e32 v4, s16, v15
	v_lshlrev_b32_e32 v4, 4, v4
	v_and_b32_e32 v4, 0xff0, v4
	v_cndmask_b32_e32 v4, v203, v4, vcc
	v_lshl_add_u32 v4, v4, 2, v0
	ds_add_u32 v4, v205 offset:16384
.Lsel_skip_77:
	v_lshrrev_b32_e32 v5, s17, v14
	v_cmp_eq_u32_e32 vcc, v5, v2
	s_cbranch_vccz .Lsel_skip_78
	v_lshrrev_b32_e32 v4, s16, v14
	v_lshlrev_b32_e32 v4, 4, v4
	v_and_b32_e32 v4, 0xff0, v4
	v_cndmask_b32_e32 v4, v203, v4, vcc
	v_lshl_add_u32 v4, v4, 2, v0
	ds_add_u32 v4, v205 offset:16384
.Lsel_skip_78:
	v_lshrrev_b32_e32 v5, s17, v17
	v_cmp_eq_u32_e32 vcc, v5, v2
	s_cbranch_vccz .Lsel_skip_79
	v_lshrrev_b32_e32 v4, s16, v17
	v_lshlrev_b32_e32 v4, 4, v4
	v_and_b32_e32 v4, 0xff0, v4
	v_cndmask_b32_e32 v4, v203, v4, vcc
	v_lshl_add_u32 v4, v4, 2, v0
	ds_add_u32 v4, v205 offset:16384
.Lsel_skip_79:
	v_or_b32_e32 v3, v3, v16
	v_lshrrev_b32_e32 v4, s17, v3
	v_lshrrev_b32_e32 v3, s16, v3
	v_lshlrev_b32_e32 v3, 4, v3
	v_and_b32_e32 v3, 0xff0, v3
	v_cmp_eq_u32_e32 vcc, v4, v2
	s_nop 1
	v_cndmask_b32_e32 v2, v203, v3, vcc
	v_lshl_add_u32 v2, v2, 2, v0
	ds_add_u32 v2, v205 offset:16384

; #define SEL_HADD(idx_) __hip_atomic_fetch_add(&hist[(idx_)], 1u, __ATOMIC_RELAXED, __HIP_MEMORY_SCOPE_WORKGROUP)
; __device__ __forceinline__ void sel_unit(LAS char* lds, int b, int u, const bf16_t* QI, const bf16_t* KIDX, const float* WIDX, unsigned long long* MASK) {
;     ...
;     for (int pass = 1; pass < 4; ++pass) {
;         const int shift = 24 - 8 * pass;
;         { const int t_ = opaque_tid(); for (int i = t_; i < 4096; i += 512) hist[i] = 0u; }
;         __syncthreads();
;         const unsigned pf = pref[q16];
;         unsigned zz = 0u; asm volatile("" : "+v"(zz));
; #pragma unroll
;         for (int j = 0; j < 8; ++j) if (j < nj) {
; #pragma unroll
;             for (int kb = 0; kb < 4; ++kb)
; #pragma unroll
;                 for (int i = 0; i < 4; ++i) { const unsigned k = sc[j][kb][i] | zz; SEL_HADD((((k >> (shift + 8)) == pf) ? ((k >> shift) & 255u) * 16 : 4096u) + q16); __builtin_amdgcn_sched_barrier(0); }
;         }
.LBB0_742:
	v_lshrrev_b32_e32 v5, s17, v94
	s_waitcnt lgkmcnt(0)
	v_cmp_eq_u32_e32 vcc, v5, v2
	s_cbranch_vccz .Lsel_skip_80
	v_lshrrev_b32_e32 v4, s16, v94
	v_lshlrev_b32_e32 v4, 4, v4
	v_and_b32_e32 v4, 0xff0, v4
	v_cndmask_b32_e32 v4, v203, v4, vcc
	v_lshl_add_u32 v4, v4, 2, v0
	ds_add_u32 v4, v205 offset:16384
.Lsel_skip_80:
	v_lshrrev_b32_e32 v5, s17, v93
	v_cmp_eq_u32_e32 vcc, v5, v2
	s_cbranch_vccz .Lsel_skip_81
	v_lshrrev_b32_e32 v4, s16, v93
	v_lshlrev_b32_e32 v4, 4, v4
	v_and_b32_e32 v4, 0xff0, v4
	v_cndmask_b32_e32 v4, v203, v4, vcc
	v_lshl_add_u32 v4, v4, 2, v0
	ds_add_u32 v4, v205 offset:16384
.Lsel_skip_81:
	v_lshrrev_b32_e32 v5, s17, v96
	v_cmp_eq_u32_e32 vcc, v5, v2
	s_cbranch_vccz .Lsel_skip_82
	v_lshrrev_b32_e32 v4, s16, v96
	v_lshlrev_b32_e32 v4, 4, v4
	v_and_b32_e32 v4, 0xff0, v4
	v_cndmask_b32_e32 v4, v203, v4, vcc
	v_lshl_add_u32 v4, v4, 2, v0
	ds_add_u32 v4, v205 offset:16384
.Lsel_skip_82:
	v_lshrrev_b32_e32 v5, s17, v95
	v_cmp_eq_u32_e32 vcc, v5, v2
	s_cbranch_vccz .Lsel_skip_83
	v_lshrrev_b32_e32 v4, s16, v95
	v_lshlrev_b32_e32 v4, 4, v4
	v_and_b32_e32 v4, 0xff0, v4
	v_cndmask_b32_e32 v4, v203, v4, vcc
	v_lshl_add_u32 v4, v4, 2, v0
	ds_add_u32 v4, v205 offset:16384
.Lsel_skip_83:
	v_lshrrev_b32_e32 v5, s17, v98
	v_cmp_eq_u32_e32 vcc, v5, v2
	s_cbranch_vccz .Lsel_skip_84
	v_lshrrev_b32_e32 v4, s16, v98
	v_lshlrev_b32_e32 v4, 4, v4
	v_and_b32_e32 v4, 0xff0, v4
	v_cndmask_b32_e32 v4, v203, v4, vcc
	v_lshl_add_u32 v4, v4, 2, v0
	ds_add_u32 v4, v205 offset:16384
.Lsel_skip_84:
	v_lshrrev_b32_e32 v5, s17, v97
	v_cmp_eq_u32_e32 vcc, v5, v2
	s_cbranch_vccz .Lsel_skip_85
	v_lshrrev_b32_e32 v4, s16, v97
	v_lshlrev_b32_e32 v4, 4, v4
	v_and_b32_e32 v4, 0xff0, v4
	v_cndmask_b32_e32 v4, v203, v4, vcc
	v_lshl_add_u32 v4, v4, 2, v0
	ds_add_u32 v4, v205 offset:16384
.Lsel_skip_85:
	v_lshrrev_b32_e32 v5, s17, v100
	v_cmp_eq_u32_e32 vcc, v5, v2
	s_cbranch_vccz .Lsel_skip_86
	v_lshrrev_b32_e32 v4, s16, v100
	v_lshlrev_b32_e32 v4, 4, v4
	v_and_b32_e32 v4, 0xff0, v4
	v_cndmask_b32_e32 v4, v203, v4, vcc
	v_lshl_add_u32 v4, v4, 2, v0
	ds_add_u32 v4, v205 offset:16384
.Lsel_skip_86:
	v_lshrrev_b32_e32 v5, s17, v99
	v_cmp_eq_u32_e32 vcc, v5, v2
	s_cbranch_vccz .Lsel_skip_87
	v_lshrrev_b32_e32 v4, s16, v99
	v_lshlrev_b32_e32 v4, 4, v4
	v_and_b32_e32 v4, 0xff0, v4
	v_cndmask_b32_e32 v4, v203, v4, vcc
	v_lshl_add_u32 v4, v4, 2, v0
	ds_add_u32 v4, v205 offset:16384
.Lsel_skip_87:
	v_lshrrev_b32_e32 v5, s17, v102
	v_cmp_eq_u32_e32 vcc, v5, v2
	s_cbranch_vccz .Lsel_skip_88
	v_lshrrev_b32_e32 v4, s16, v102
	v_lshlrev_b32_e32 v4, 4, v4
	v_and_b32_e32 v4, 0xff0, v4
	v_cndmask_b32_e32 v4, v203, v4, vcc
	v_lshl_add_u32 v4, v4, 2, v0
	ds_add_u32 v4, v205 offset:16384
.Lsel_skip_88:
	v_lshrrev_b32_e32 v5, s17, v101
	v_cmp_eq_u32_e32 vcc, v5, v2
	s_cbranch_vccz .Lsel_skip_89
	v_lshrrev_b32_e32 v4, s16, v101
	v_lshlrev_b32_e32 v4, 4, v4
	v_and_b32_e32 v4, 0xff0, v4
	v_cndmask_b32_e32 v4, v203, v4, vcc
	v_lshl_add_u32 v4, v4, 2, v0
	ds_add_u32 v4, v205 offset:16384
.Lsel_skip_89:
	v_lshrrev_b32_e32 v5, s17, v104
	v_cmp_eq_u32_e32 vcc, v5, v2
	s_cbranch_vccz .Lsel_skip_90
	v_lshrrev_b32_e32 v4, s16, v104
	v_lshlrev_b32_e32 v4, 4, v4
	v_and_b32_e32 v4, 0xff0, v4
	v_cndmask_b32_e32 v4, v203, v4, vcc
	v_lshl_add_u32 v4, v4, 2, v0
	ds_add_u32 v4, v205 offset:16384
.Lsel_skip_90:
	v_lshrrev_b32_e32 v5, s17, v103
	v_cmp_eq_u32_e32 vcc, v5, v2
	s_cbranch_vccz .Lsel_skip_91
	v_lshrrev_b32_e32 v4, s16, v103
	v_lshlrev_b32_e32 v4, 4, v4
	v_and_b32_e32 v4, 0xff0, v4
	v_cndmask_b32_e32 v4, v203, v4, vcc
	v_lshl_add_u32 v4, v4, 2, v0
	ds_add_u32 v4, v205 offset:16384
.Lsel_skip_91:
	v_lshrrev_b32_e32 v5, s17, v106
	v_cmp_eq_u32_e32 vcc, v5, v2
	s_cbranch_vccz .Lsel_skip_92
	v_lshrrev_b32_e32 v4, s16, v106
	v_lshlrev_b32_e32 v4, 4, v4
	v_and_b32_e32 v4, 0xff0, v4
	v_cndmask_b32_e32 v4, v203, v4, vcc
	v_lshl_add_u32 v4, v4, 2, v0
	ds_add_u32 v4, v205 offset:16384
.Lsel_skip_92:
	v_lshrrev_b32_e32 v5, s17, v105
	v_cmp_eq_u32_e32 vcc, v5, v2
	s_cbranch_vccz .Lsel_skip_93
	v_lshrrev_b32_e32 v4, s16, v105
	v_lshlrev_b32_e32 v4, 4, v4
	v_and_b32_e32 v4, 0xff0, v4
	v_cndmask_b32_e32 v4, v203, v4, vcc
	v_lshl_add_u32 v4, v4, 2, v0
	ds_add_u32 v4, v205 offset:16384
.Lsel_skip_93:
	v_lshrrev_b32_e32 v5, s17, v108
	v_cmp_eq_u32_e32 vcc, v5, v2
	s_cbranch_vccz .Lsel_skip_94
	v_lshrrev_b32_e32 v4, s16, v108
	v_lshlrev_b32_e32 v4, 4, v4
	v_and_b32_e32 v4, 0xff0, v4
	v_cndmask_b32_e32 v4, v203, v4, vcc
	v_lshl_add_u32 v4, v4, 2, v0
	ds_add_u32 v4, v205 offset:16384
.Lsel_skip_94:
	v_lshrrev_b32_e32 v5, s17, v107
	v_cmp_eq_u32_e32 vcc, v5, v2
	s_cbranch_vccz .Lsel_skip_95
	v_lshrrev_b32_e32 v4, s16, v107
	v_lshlrev_b32_e32 v4, 4, v4
	v_and_b32_e32 v4, 0xff0, v4
	v_cndmask_b32_e32 v4, v203, v4, vcc
	v_lshl_add_u32 v4, v4, 2, v0
	ds_add_u32 v4, v205 offset:16384
.Lsel_skip_95:
	v_cndmask_b32_e64 v4, 0, 1, s[56:57]
	v_cmp_ne_u32_e64 s[6:7], 1, v4
	s_andn2_b64 vcc, exec, s[56:57]
	s_cbranch_vccz .LBB0_714

; #define SEL_HADD(idx_) __hip_atomic_fetch_add(&hist[(idx_)], 1u, __ATOMIC_RELAXED, __HIP_MEMORY_SCOPE_WORKGROUP)
; __device__ __forceinline__ void sel_unit(LAS char* lds, int b, int u, const bf16_t* QI, const bf16_t* KIDX, const float* WIDX, unsigned long long* MASK) {
;     ...
;     for (int pass = 1; pass < 4; ++pass) {
;         const int shift = 24 - 8 * pass;
;         { const int t_ = opaque_tid(); for (int i = t_; i < 4096; i += 512) hist[i] = 0u; }
;         __syncthreads();
;         const unsigned pf = pref[q16];
;         unsigned zz = 0u; asm volatile("" : "+v"(zz));
; #pragma unroll
;         for (int j = 0; j < 8; ++j) if (j < nj) {
; #pragma unroll
;             for (int kb = 0; kb < 4; ++kb)
; #pragma unroll
;                 for (int i = 0; i < 4; ++i) { const unsigned k = sc[j][kb][i] | zz; SEL_HADD((((k >> (shift + 8)) == pf) ? ((k >> shift) & 255u) * 16 : 4096u) + q16); __builtin_amdgcn_sched_barrier(0); }
;         }
.LBB0_744:
	v_lshrrev_b32_e32 v5, s17, v126
	s_waitcnt lgkmcnt(0)
	v_cmp_eq_u32_e32 vcc, v5, v2
	s_cbranch_vccz .Lsel_skip_96
	v_lshrrev_b32_e32 v4, s16, v126
	v_lshlrev_b32_e32 v4, 4, v4
	v_and_b32_e32 v4, 0xff0, v4
	v_cndmask_b32_e32 v4, v203, v4, vcc
	v_lshl_add_u32 v4, v4, 2, v0
	ds_add_u32 v4, v205 offset:16384
.Lsel_skip_96:
	v_lshrrev_b32_e32 v5, s17, v125
	v_cmp_eq_u32_e32 vcc, v5, v2
	s_cbranch_vccz .Lsel_skip_97
	v_lshrrev_b32_e32 v4, s16, v125
	v_lshlrev_b32_e32 v4, 4, v4
	v_and_b32_e32 v4, 0xff0, v4
	v_cndmask_b32_e32 v4, v203, v4, vcc
	v_lshl_add_u32 v4, v4, 2, v0
	ds_add_u32 v4, v205 offset:16384
.Lsel_skip_97:
	v_lshrrev_b32_e32 v5, s17, v128
	v_cmp_eq_u32_e32 vcc, v5, v2
	s_cbranch_vccz .Lsel_skip_98
	v_lshrrev_b32_e32 v4, s16, v128
	v_lshlrev_b32_e32 v4, 4, v4
	v_and_b32_e32 v4, 0xff0, v4
	v_cndmask_b32_e32 v4, v203, v4, vcc
	v_lshl_add_u32 v4, v4, 2, v0
	ds_add_u32 v4, v205 offset:16384
.Lsel_skip_98:
	v_lshrrev_b32_e32 v5, s17, v127
	v_cmp_eq_u32_e32 vcc, v5, v2
	s_cbranch_vccz .Lsel_skip_99
	v_lshrrev_b32_e32 v4, s16, v127
	v_lshlrev_b32_e32 v4, 4, v4
	v_and_b32_e32 v4, 0xff0, v4
	v_cndmask_b32_e32 v4, v203, v4, vcc
	v_lshl_add_u32 v4, v4, 2, v0
	ds_add_u32 v4, v205 offset:16384
.Lsel_skip_99:
	v_lshrrev_b32_e32 v5, s17, v130
	v_cmp_eq_u32_e32 vcc, v5, v2
	s_cbranch_vccz .Lsel_skip_100
	v_lshrrev_b32_e32 v4, s16, v130
	v_lshlrev_b32_e32 v4, 4, v4
	v_and_b32_e32 v4, 0xff0, v4
	v_cndmask_b32_e32 v4, v203, v4, vcc
	v_lshl_add_u32 v4, v4, 2, v0
	ds_add_u32 v4, v205 offset:16384
.Lsel_skip_100:
	v_lshrrev_b32_e32 v5, s17, v129
	v_cmp_eq_u32_e32 vcc, v5, v2
	s_cbranch_vccz .Lsel_skip_101
	v_lshrrev_b32_e32 v4, s16, v129
	v_lshlrev_b32_e32 v4, 4, v4
	v_and_b32_e32 v4, 0xff0, v4
	v_cndmask_b32_e32 v4, v203, v4, vcc
	v_lshl_add_u32 v4, v4, 2, v0
	ds_add_u32 v4, v205 offset:16384
.Lsel_skip_101:
	v_lshrrev_b32_e32 v5, s17, v132
	v_cmp_eq_u32_e32 vcc, v5, v2
	s_cbranch_vccz .Lsel_skip_102
	v_lshrrev_b32_e32 v4, s16, v132
	v_lshlrev_b32_e32 v4, 4, v4
	v_and_b32_e32 v4, 0xff0, v4
	v_cndmask_b32_e32 v4, v203, v4, vcc
	v_lshl_add_u32 v4, v4, 2, v0
	ds_add_u32 v4, v205 offset:16384
.Lsel_skip_102:
	v_lshrrev_b32_e32 v5, s17, v131
	v_cmp_eq_u32_e32 vcc, v5, v2
	s_cbranch_vccz .Lsel_skip_103
	v_lshrrev_b32_e32 v4, s16, v131
	v_lshlrev_b32_e32 v4, 4, v4
	v_and_b32_e32 v4, 0xff0, v4
	v_cndmask_b32_e32 v4, v203, v4, vcc
	v_lshl_add_u32 v4, v4, 2, v0
	ds_add_u32 v4, v205 offset:16384
.Lsel_skip_103:
	v_lshrrev_b32_e32 v5, s17, v134
	v_cmp_eq_u32_e32 vcc, v5, v2
	s_cbranch_vccz .Lsel_skip_104
	v_lshrrev_b32_e32 v4, s16, v134
	v_lshlrev_b32_e32 v4, 4, v4
	v_and_b32_e32 v4, 0xff0, v4
	v_cndmask_b32_e32 v4, v203, v4, vcc
	v_lshl_add_u32 v4, v4, 2, v0
	ds_add_u32 v4, v205 offset:16384
.Lsel_skip_104:
	v_lshrrev_b32_e32 v5, s17, v133
	v_cmp_eq_u32_e32 vcc, v5, v2
	s_cbranch_vccz .Lsel_skip_105
	v_lshrrev_b32_e32 v4, s16, v133
	v_lshlrev_b32_e32 v4, 4, v4
	v_and_b32_e32 v4, 0xff0, v4
	v_cndmask_b32_e32 v4, v203, v4, vcc
	v_lshl_add_u32 v4, v4, 2, v0
	ds_add_u32 v4, v205 offset:16384
.Lsel_skip_105:
	v_lshrrev_b32_e32 v5, s17, v136
	v_cmp_eq_u32_e32 vcc, v5, v2
	s_cbranch_vccz .Lsel_skip_106
	v_lshrrev_b32_e32 v4, s16, v136
	v_lshlrev_b32_e32 v4, 4, v4
	v_and_b32_e32 v4, 0xff0, v4
	v_cndmask_b32_e32 v4, v203, v4, vcc
	v_lshl_add_u32 v4, v4, 2, v0
	ds_add_u32 v4, v205 offset:16384
.Lsel_skip_106:
	v_lshrrev_b32_e32 v5, s17, v135
	v_cmp_eq_u32_e32 vcc, v5, v2
	s_cbranch_vccz .Lsel_skip_107
	v_lshrrev_b32_e32 v4, s16, v135
	v_lshlrev_b32_e32 v4, 4, v4
	v_and_b32_e32 v4, 0xff0, v4
	v_cndmask_b32_e32 v4, v203, v4, vcc
	v_lshl_add_u32 v4, v4, 2, v0
	ds_add_u32 v4, v205 offset:16384
.Lsel_skip_107:
	v_lshrrev_b32_e32 v5, s17, v139
	v_cmp_eq_u32_e32 vcc, v5, v2
	s_cbranch_vccz .Lsel_skip_108
	v_lshrrev_b32_e32 v4, s16, v139
	v_lshlrev_b32_e32 v4, 4, v4
	v_and_b32_e32 v4, 0xff0, v4
	v_cndmask_b32_e32 v4, v203, v4, vcc
	v_lshl_add_u32 v4, v4, 2, v0
	ds_add_u32 v4, v205 offset:16384
.Lsel_skip_108:
	v_lshrrev_b32_e32 v5, s17, v138
	v_cmp_eq_u32_e32 vcc, v5, v2
	s_cbranch_vccz .Lsel_skip_109
	v_lshrrev_b32_e32 v4, s16, v138
	v_lshlrev_b32_e32 v4, 4, v4
	v_and_b32_e32 v4, 0xff0, v4
	v_cndmask_b32_e32 v4, v203, v4, vcc
	v_lshl_add_u32 v4, v4, 2, v0
	ds_add_u32 v4, v205 offset:16384
.Lsel_skip_109:
	v_lshrrev_b32_e32 v5, s17, v141
	v_cmp_eq_u32_e32 vcc, v5, v2
	s_cbranch_vccz .Lsel_skip_110
	v_lshrrev_b32_e32 v4, s16, v141
	v_lshlrev_b32_e32 v4, 4, v4
	v_and_b32_e32 v4, 0xff0, v4
	v_cndmask_b32_e32 v4, v203, v4, vcc
	v_lshl_add_u32 v4, v4, 2, v0
	ds_add_u32 v4, v205 offset:16384
.Lsel_skip_110:
	v_lshrrev_b32_e32 v5, s17, v140
	v_cmp_eq_u32_e32 vcc, v5, v2
	s_cbranch_vccz .Lsel_skip_111
	v_lshrrev_b32_e32 v4, s16, v140
	v_lshlrev_b32_e32 v4, 4, v4
	v_and_b32_e32 v4, 0xff0, v4
	v_cndmask_b32_e32 v4, v203, v4, vcc
	v_lshl_add_u32 v4, v4, 2, v0
	ds_add_u32 v4, v205 offset:16384
.Lsel_skip_111:
	v_cndmask_b32_e64 v4, 0, 1, s[48:49]
	v_cmp_ne_u32_e64 s[10:11], 1, v4
	s_andn2_b64 vcc, exec, s[48:49]
	s_cbranch_vccz .LBB0_716

; #define SEL_HADD(idx_) __hip_atomic_fetch_add(&hist[(idx_)], 1u, __ATOMIC_RELAXED, __HIP_MEMORY_SCOPE_WORKGROUP)
; __device__ __forceinline__ void sel_unit(LAS char* lds, int b, int u, const bf16_t* QI, const bf16_t* KIDX, const float* WIDX, unsigned long long* MASK) {
;     ...
;     for (int pass = 1; pass < 4; ++pass) {
;         const int shift = 24 - 8 * pass;
;         { const int t_ = opaque_tid(); for (int i = t_; i < 4096; i += 512) hist[i] = 0u; }
;         __syncthreads();
;         const unsigned pf = pref[q16];
;         unsigned zz = 0u; asm volatile("" : "+v"(zz));
; #pragma unroll
;         for (int j = 0; j < 8; ++j) if (j < nj) {
; #pragma unroll
;             for (int kb = 0; kb < 4; ++kb)
; #pragma unroll
;                 for (int i = 0; i < 4; ++i) { const unsigned k = sc[j][kb][i] | zz; SEL_HADD((((k >> (shift + 8)) == pf) ? ((k >> shift) & 255u) * 16 : 4096u) + q16); __builtin_amdgcn_sched_barrier(0); }
;         }
.LBB0_746:
	v_lshrrev_b32_e32 v5, s17, v192
	s_waitcnt lgkmcnt(0)
	v_cmp_eq_u32_e32 vcc, v5, v2
	s_cbranch_vccz .Lsel_skip_112
	v_lshrrev_b32_e32 v4, s16, v192
	v_lshlrev_b32_e32 v4, 4, v4
	v_and_b32_e32 v4, 0xff0, v4
	v_cndmask_b32_e32 v4, v203, v4, vcc
	v_lshl_add_u32 v4, v4, 2, v0
	ds_add_u32 v4, v205 offset:16384
.Lsel_skip_112:
	v_lshrrev_b32_e32 v5, s17, v191
	v_cmp_eq_u32_e32 vcc, v5, v2
	s_cbranch_vccz .Lsel_skip_113
	v_lshrrev_b32_e32 v4, s16, v191
	v_lshlrev_b32_e32 v4, 4, v4
	v_and_b32_e32 v4, 0xff0, v4
	v_cndmask_b32_e32 v4, v203, v4, vcc
	v_lshl_add_u32 v4, v4, 2, v0
	ds_add_u32 v4, v205 offset:16384
.Lsel_skip_113:
	v_lshrrev_b32_e32 v5, s17, v194
	v_cmp_eq_u32_e32 vcc, v5, v2
	s_cbranch_vccz .Lsel_skip_114
	v_lshrrev_b32_e32 v4, s16, v194
	v_lshlrev_b32_e32 v4, 4, v4
	v_and_b32_e32 v4, 0xff0, v4
	v_cndmask_b32_e32 v4, v203, v4, vcc
	v_lshl_add_u32 v4, v4, 2, v0
	ds_add_u32 v4, v205 offset:16384
.Lsel_skip_114:
	v_lshrrev_b32_e32 v5, s17, v193
	v_cmp_eq_u32_e32 vcc, v5, v2
	s_cbranch_vccz .Lsel_skip_115
	v_lshrrev_b32_e32 v4, s16, v193
	v_lshlrev_b32_e32 v4, 4, v4
	v_and_b32_e32 v4, 0xff0, v4
	v_cndmask_b32_e32 v4, v203, v4, vcc
	v_lshl_add_u32 v4, v4, 2, v0
	ds_add_u32 v4, v205 offset:16384
.Lsel_skip_115:
	v_lshrrev_b32_e32 v5, s17, v196
	v_cmp_eq_u32_e32 vcc, v5, v2
	s_cbranch_vccz .Lsel_skip_116
	v_lshrrev_b32_e32 v4, s16, v196
	v_lshlrev_b32_e32 v4, 4, v4
	v_and_b32_e32 v4, 0xff0, v4
	v_cndmask_b32_e32 v4, v203, v4, vcc
	v_lshl_add_u32 v4, v4, 2, v0
	ds_add_u32 v4, v205 offset:16384
.Lsel_skip_116:
	v_lshrrev_b32_e32 v5, s17, v195
	v_cmp_eq_u32_e32 vcc, v5, v2
	s_cbranch_vccz .Lsel_skip_117
	v_lshrrev_b32_e32 v4, s16, v195
	v_lshlrev_b32_e32 v4, 4, v4
	v_and_b32_e32 v4, 0xff0, v4
	v_cndmask_b32_e32 v4, v203, v4, vcc
	v_lshl_add_u32 v4, v4, 2, v0
	ds_add_u32 v4, v205 offset:16384
.Lsel_skip_117:
	v_lshrrev_b32_e32 v5, s17, v198
	v_cmp_eq_u32_e32 vcc, v5, v2
	s_cbranch_vccz .Lsel_skip_118
	v_lshrrev_b32_e32 v4, s16, v198
	v_lshlrev_b32_e32 v4, 4, v4
	v_and_b32_e32 v4, 0xff0, v4
	v_cndmask_b32_e32 v4, v203, v4, vcc
	v_lshl_add_u32 v4, v4, 2, v0
	ds_add_u32 v4, v205 offset:16384
.Lsel_skip_118:
	v_lshrrev_b32_e32 v5, s17, v197
	v_cmp_eq_u32_e32 vcc, v5, v2
	s_cbranch_vccz .Lsel_skip_119
	v_lshrrev_b32_e32 v4, s16, v197
	v_lshlrev_b32_e32 v4, 4, v4
	v_and_b32_e32 v4, 0xff0, v4
	v_cndmask_b32_e32 v4, v203, v4, vcc
	v_lshl_add_u32 v4, v4, 2, v0
	ds_add_u32 v4, v205 offset:16384
.Lsel_skip_119:
	v_lshrrev_b32_e32 v5, s17, v57
	v_cmp_eq_u32_e32 vcc, v5, v2
	s_cbranch_vccz .Lsel_skip_120
	v_lshrrev_b32_e32 v4, s16, v57
	v_lshlrev_b32_e32 v4, 4, v4
	v_and_b32_e32 v4, 0xff0, v4
	v_cndmask_b32_e32 v4, v203, v4, vcc
	v_lshl_add_u32 v4, v4, 2, v0
	ds_add_u32 v4, v205 offset:16384
.Lsel_skip_120:
	v_lshrrev_b32_e32 v5, s17, v56
	v_cmp_eq_u32_e32 vcc, v5, v2
	s_cbranch_vccz .Lsel_skip_121
	v_lshrrev_b32_e32 v4, s16, v56
	v_lshlrev_b32_e32 v4, 4, v4
	v_and_b32_e32 v4, 0xff0, v4
	v_cndmask_b32_e32 v4, v203, v4, vcc
	v_lshl_add_u32 v4, v4, 2, v0
	ds_add_u32 v4, v205 offset:16384
.Lsel_skip_121:
	v_lshrrev_b32_e32 v5, s17, v55
	v_cmp_eq_u32_e32 vcc, v5, v2
	s_cbranch_vccz .Lsel_skip_122
	v_lshrrev_b32_e32 v4, s16, v55
	v_lshlrev_b32_e32 v4, 4, v4
	v_and_b32_e32 v4, 0xff0, v4
	v_cndmask_b32_e32 v4, v203, v4, vcc
	v_lshl_add_u32 v4, v4, 2, v0
	ds_add_u32 v4, v205 offset:16384
.Lsel_skip_122:
	v_lshrrev_b32_e32 v5, s17, v54
	v_cmp_eq_u32_e32 vcc, v5, v2
	s_cbranch_vccz .Lsel_skip_123
	v_lshrrev_b32_e32 v4, s16, v54
	v_lshlrev_b32_e32 v4, 4, v4
	v_and_b32_e32 v4, 0xff0, v4
	v_cndmask_b32_e32 v4, v203, v4, vcc
	v_lshl_add_u32 v4, v4, 2, v0
	ds_add_u32 v4, v205 offset:16384
.Lsel_skip_123:
	v_lshrrev_b32_e32 v5, s17, v218
	v_cmp_eq_u32_e32 vcc, v5, v2
	s_cbranch_vccz .Lsel_skip_124
	v_lshrrev_b32_e32 v4, s16, v218
	v_lshlrev_b32_e32 v4, 4, v4
	v_and_b32_e32 v4, 0xff0, v4
	v_cndmask_b32_e32 v4, v203, v4, vcc
	v_lshl_add_u32 v4, v4, 2, v0
	ds_add_u32 v4, v205 offset:16384
.Lsel_skip_124:
	v_lshrrev_b32_e32 v5, s17, v199
	v_cmp_eq_u32_e32 vcc, v5, v2
	s_cbranch_vccz .Lsel_skip_125
	v_lshrrev_b32_e32 v4, s16, v199
	v_lshlrev_b32_e32 v4, 4, v4
	v_and_b32_e32 v4, 0xff0, v4
	v_cndmask_b32_e32 v4, v203, v4, vcc
	v_lshl_add_u32 v4, v4, 2, v0
	ds_add_u32 v4, v205 offset:16384
.Lsel_skip_125:
	v_lshrrev_b32_e32 v5, s17, v220
	v_cmp_eq_u32_e32 vcc, v5, v2
	s_cbranch_vccz .Lsel_skip_126
	v_lshrrev_b32_e32 v4, s16, v220
	v_lshlrev_b32_e32 v4, 4, v4
	v_and_b32_e32 v4, 0xff0, v4
	v_cndmask_b32_e32 v4, v203, v4, vcc
	v_lshl_add_u32 v4, v4, 2, v0
	ds_add_u32 v4, v205 offset:16384
.Lsel_skip_126:
	v_lshrrev_b32_e32 v5, s17, v219
	v_cmp_eq_u32_e32 vcc, v5, v2
	s_cbranch_vccz .Lsel_skip_127
	v_lshrrev_b32_e32 v4, s16, v219
	v_lshlrev_b32_e32 v4, 4, v4
	v_and_b32_e32 v4, 0xff0, v4
	v_cndmask_b32_e32 v4, v203, v4, vcc
	v_lshl_add_u32 v4, v4, 2, v0
	ds_add_u32 v4, v205 offset:16384
.Lsel_skip_127:
	v_cndmask_b32_e64 v4, 0, 1, s[26:27]
	v_cmp_ne_u32_e64 s[14:15], 1, v4
	s_andn2_b64 vcc, exec, s[26:27]
	s_cbranch_vccz .LBB0_718
	s_branch .LBB0_719
